# speedup vs baseline: 1.0083x; 1.0083x over previous
; __device__ __forceinline__ unsigned cvt_pk_bf16(float lo, float hi) { unsigned r; asm volatile("v_cvt_pk_bf16_f32 %0, %1, %2" : "=v"(r) : "v"(lo), "v"(hi)); return r; }
;     __device__ __forceinline__ void operator()(const f32x4 (&acc)[2][2][4][2], const Unit& u, int wr, int wc, int fr, int fq) const {
;     ...
;         const int col0 = u.pn * HALF + wc * 32 + 8 * fq;
; #pragma unroll
;         for (int ai = 0; ai < 2; ++ai)
; #pragma unroll
;             for (int m = 0; m < 4; ++m) { bf16_t* rowp = O + (size_t)(row0 + ai * HALF + m * 16) * ldc + col0;
;                 f32x2 h[4];
; #pragma unroll
;                 for (int n = 0; n < 2; ++n)
; #pragma unroll
;                     for (int j = 0; j < 2; ++j) { const f32x2 g = {acc[ai][0][m][n][2 * j], acc[ai][0][m][n][2 * j + 1]}, up = {acc[ai][1][m][n][2 * j], acc[ai][1][m][n][2 * j + 1]};
;                         const f32x2 t = g * (-1.44269504089f); f32x2 e; e.x = __builtin_amdgcn_exp2f(t.x); e.y = __builtin_amdgcn_exp2f(t.y);
;                         const f32x2 d = e + 1.0f; f32x2 r; r.x = __builtin_amdgcn_rcpf(d.x); r.y = __builtin_amdgcn_rcpf(d.y);
;                         h[n * 2 + j] = (g * r) * up; }
;                 u32x4 w; w.x = cvt_pk_bf16(h[0].x, h[0].y); w.y = cvt_pk_bf16(h[1].x, h[1].y); w.z = cvt_pk_bf16(h[2].x, h[2].y); w.w = cvt_pk_bf16(h[3].x, h[3].y);
;                 *(u32x4*)rowp = w; }
.LBB0_362:
	v_lshrrev_b32_e32 v254, 2, v206
	v_and_b32_e32 v255, 15, v206
	v_sub_u32_e32 v252, v254, v255
	v_mul_lo_u32 v252, v252, s20
	v_lshlrev_b32_e32 v252, 1, v252
	v_and_b32_e32 v253, 3, v206
	v_lshrrev_b32_e32 v255, 4, v206
	v_sub_u32_e32 v253, v253, v255
	v_lshl_add_u32 v252, v253, 4, v252
	v_ashrrev_i32_e32 v253, 31, v252
	v_lshrrev_b32_e32 v255, 6, v180
	v_mul_u32_u24_e32 v255, 0x500, v255
	v_add_u32_e32 v255, 0x20000, v255
	v_and_b32_e32 v244, 15, v206
	v_mul_u32_u24_e32 v244, 0x50, v244
	v_lshrrev_b32_e32 v245, 4, v206
	v_lshl_add_u32 v244, v245, 4, v244
	v_add_u32_e32 v244, v244, v255
	v_mul_u32_u24_e32 v245, 0x50, v254
	v_and_b32_e32 v254, 3, v206
	v_lshl_add_u32 v245, v254, 4, v245
	v_add_u32_e32 v245, v245, v255
	v_lshl_add_u32 v148, s31, 8, v144
	s_cmp_lt_i32 s30, 0
	s_mov_b64 s[38:39], -1
	s_mov_b32 s60, 0x14000
	s_cbranch_scc0 .LBB0_369
	v_mad_i64_i32 v[140:141], s[18:19], s20, v148, 0
	v_lshl_add_u64 v[140:141], v[140:141], 1, s[8:9]
	s_and_b64 vcc, exec, s[26:27]
	v_or_b32_e32 v155, 16, v148
	v_or_b32_e32 v154, 32, v148
	v_or_b32_e32 v153, 48, v148
	v_add_u32_e32 v152, 0x80, v148
	v_add_u32_e32 v151, 0x90, v148
	v_add_u32_e32 v150, 0xa0, v148
	v_add_u32_e32 v149, 0xb0, v148
	s_cbranch_vccz .LBB0_365
	v_pk_mul_f32 v[156:157], v[126:127], s[92:93] op_sel_hi:[1,0]
	v_pk_mul_f32 v[158:159], v[128:129], s[92:93] op_sel_hi:[1,0]
	v_exp_f32_e32 v156, v156
	v_exp_f32_e32 v157, v157
	v_exp_f32_e32 v158, v158
	v_exp_f32_e32 v159, v159
	v_pk_mul_f32 v[160:161], v[122:123], s[92:93] op_sel_hi:[1,0]
	v_pk_mul_f32 v[162:163], v[124:125], s[92:93] op_sel_hi:[1,0]
	v_exp_f32_e32 v160, v160
	v_exp_f32_e32 v161, v161
	v_exp_f32_e32 v162, v162
	v_exp_f32_e32 v163, v163
	v_pk_add_f32 v[156:157], v[156:157], 1.0 op_sel_hi:[1,0]
	v_pk_add_f32 v[158:159], v[158:159], 1.0 op_sel_hi:[1,0]
	v_rcp_f32_e32 v156, v156
	v_rcp_f32_e32 v157, v157
	v_rcp_f32_e32 v158, v158
	v_rcp_f32_e32 v159, v159
	v_pk_add_f32 v[160:161], v[160:161], 1.0 op_sel_hi:[1,0]
	v_pk_add_f32 v[162:163], v[162:163], 1.0 op_sel_hi:[1,0]
	v_rcp_f32_e32 v160, v160
	v_rcp_f32_e32 v161, v161
	v_rcp_f32_e32 v162, v162
	v_rcp_f32_e32 v163, v163
	v_lshl_or_b32 v142, s67, 7, v146
	v_ashrrev_i32_e32 v143, 31, v142
	v_pk_mul_f32 v[156:157], v[126:127], v[156:157]
	v_pk_mul_f32 v[158:159], v[128:129], v[158:159]
	v_pk_mul_f32 v[156:157], v[114:115], v[156:157]
	v_pk_mul_f32 v[158:159], v[116:117], v[158:159]
	v_pk_mul_f32 v[160:161], v[122:123], v[160:161]
	v_pk_mul_f32 v[162:163], v[124:125], v[162:163]
	v_lshlrev_b64 v[142:143], 1, v[142:143]
	v_pk_mul_f32 v[160:161], v[106:107], v[160:161]
	v_pk_mul_f32 v[162:163], v[108:109], v[162:163]
	v_lshl_add_u64 v[164:165], v[140:141], 0, v[142:143]
	v_cvt_pk_bf16_f32 v156, v156, v157
	v_cvt_pk_bf16_f32 v157, v158, v159
	v_cvt_pk_bf16_f32 v158, v160, v161
	v_cvt_pk_bf16_f32 v159, v162, v163
	ds_write_b128 v244, v[156:159]
	v_lshl_add_u64 v[176:177], v[164:165], 0, v[252:253]
	ds_read_b128 v[168:171], v245
	v_pk_mul_f32 v[160:161], v[120:121], s[92:93] op_sel_hi:[1,0]
	v_pk_mul_f32 v[162:163], v[110:111], s[92:93] op_sel_hi:[1,0]
	v_pk_mul_f32 v[158:159], v[118:119], s[92:93] op_sel_hi:[1,0]
	v_pk_mul_f32 v[164:165], v[112:113], s[92:93] op_sel_hi:[1,0]
	v_exp_f32_e32 v158, v158
	v_exp_f32_e32 v159, v159
	v_exp_f32_e32 v160, v160
	v_exp_f32_e32 v161, v161
	v_exp_f32_e32 v162, v162
	v_exp_f32_e32 v163, v163
	v_exp_f32_e32 v164, v164
	v_exp_f32_e32 v165, v165
	v_pk_add_f32 v[158:159], v[158:159], 1.0 op_sel_hi:[1,0]
	v_pk_add_f32 v[160:161], v[160:161], 1.0 op_sel_hi:[1,0]
	v_rcp_f32_e32 v158, v158
	v_rcp_f32_e32 v159, v159
	v_pk_add_f32 v[162:163], v[162:163], 1.0 op_sel_hi:[1,0]
	v_pk_add_f32 v[164:165], v[164:165], 1.0 op_sel_hi:[1,0]
	v_rcp_f32_e32 v160, v160
	v_rcp_f32_e32 v161, v161
	v_rcp_f32_e32 v162, v162
	v_rcp_f32_e32 v163, v163
	v_rcp_f32_e32 v164, v164
	v_rcp_f32_e32 v165, v165
	v_mad_i64_i32 v[156:157], s[18:19], s20, v155, 0
	v_pk_mul_f32 v[158:159], v[118:119], v[158:159]
	v_lshl_add_u64 v[156:157], v[156:157], 1, s[8:9]
	v_pk_mul_f32 v[158:159], v[98:99], v[158:159]
	v_pk_mul_f32 v[160:161], v[120:121], v[160:161]
	v_pk_mul_f32 v[162:163], v[110:111], v[162:163]
	v_pk_mul_f32 v[164:165], v[112:113], v[164:165]
	v_pk_mul_f32 v[160:161], v[100:101], v[160:161]
	v_pk_mul_f32 v[162:163], v[90:91], v[162:163]
	v_pk_mul_f32 v[164:165], v[92:93], v[164:165]
	v_lshl_add_u64 v[166:167], v[156:157], 0, v[142:143]
	v_cvt_pk_bf16_f32 v156, v158, v159
	v_cvt_pk_bf16_f32 v157, v160, v161
	v_cvt_pk_bf16_f32 v158, v162, v163
	v_cvt_pk_bf16_f32 v159, v164, v165
	ds_write_b128 v244, v[156:159]
	v_lshl_add_u64 v[178:179], v[166:167], 0, v[252:253]
	ds_read_b128 v[172:175], v245
	s_waitcnt lgkmcnt(2)
	global_store_dwordx4 v[176:177], v[168:171], off
	v_pk_mul_f32 v[160:161], v[104:105], s[92:93] op_sel_hi:[1,0]
	v_pk_mul_f32 v[162:163], v[94:95], s[92:93] op_sel_hi:[1,0]
	v_pk_mul_f32 v[158:159], v[102:103], s[92:93] op_sel_hi:[1,0]
	v_pk_mul_f32 v[164:165], v[96:97], s[92:93] op_sel_hi:[1,0]
	v_exp_f32_e32 v158, v158
	v_exp_f32_e32 v159, v159
	v_exp_f32_e32 v160, v160
	v_exp_f32_e32 v161, v161
	v_exp_f32_e32 v162, v162
	v_exp_f32_e32 v163, v163
	v_exp_f32_e32 v164, v164
	v_exp_f32_e32 v165, v165
	v_pk_add_f32 v[158:159], v[158:159], 1.0 op_sel_hi:[1,0]
	v_pk_add_f32 v[160:161], v[160:161], 1.0 op_sel_hi:[1,0]
	v_rcp_f32_e32 v158, v158
	v_rcp_f32_e32 v159, v159
	v_pk_add_f32 v[162:163], v[162:163], 1.0 op_sel_hi:[1,0]
	v_pk_add_f32 v[164:165], v[164:165], 1.0 op_sel_hi:[1,0]
	v_rcp_f32_e32 v160, v160
	v_rcp_f32_e32 v161, v161
	v_rcp_f32_e32 v162, v162
	v_rcp_f32_e32 v163, v163
	v_rcp_f32_e32 v164, v164
	v_rcp_f32_e32 v165, v165
	v_mad_i64_i32 v[156:157], s[18:19], s20, v154, 0
	v_pk_mul_f32 v[158:159], v[102:103], v[158:159]
	v_lshl_add_u64 v[156:157], v[156:157], 1, s[8:9]
	v_pk_mul_f32 v[158:159], v[82:83], v[158:159]
	v_pk_mul_f32 v[160:161], v[104:105], v[160:161]
	v_pk_mul_f32 v[162:163], v[94:95], v[162:163]
	v_pk_mul_f32 v[164:165], v[96:97], v[164:165]
	v_pk_mul_f32 v[160:161], v[84:85], v[160:161]
	v_pk_mul_f32 v[162:163], v[74:75], v[162:163]
	v_pk_mul_f32 v[164:165], v[76:77], v[164:165]
	v_lshl_add_u64 v[166:167], v[156:157], 0, v[142:143]
	v_cvt_pk_bf16_f32 v156, v158, v159
	v_cvt_pk_bf16_f32 v157, v160, v161
	v_cvt_pk_bf16_f32 v158, v162, v163
	v_cvt_pk_bf16_f32 v159, v164, v165
	ds_write_b128 v244, v[156:159]
	v_lshl_add_u64 v[176:177], v[166:167], 0, v[252:253]
	ds_read_b128 v[168:171], v245
	s_waitcnt lgkmcnt(2)
; __device__ __forceinline__ unsigned cvt_pk_bf16(float lo, float hi) { unsigned r; asm volatile("v_cvt_pk_bf16_f32 %0, %1, %2" : "=v"(r) : "v"(lo), "v"(hi)); return r; }
;     __device__ __forceinline__ void operator()(const f32x4 (&acc)[2][2][4][2], const Unit& u, int wr, int wc, int fr, int fq) const {
;     ...
;         const int col0 = u.pn * HALF + wc * 32 + 8 * fq;
; #pragma unroll
;         for (int ai = 0; ai < 2; ++ai)
; #pragma unroll
;             for (int m = 0; m < 4; ++m) { bf16_t* rowp = O + (size_t)(row0 + ai * HALF + m * 16) * ldc + col0;
;                 f32x2 h[4];
; #pragma unroll
;                 for (int n = 0; n < 2; ++n)
; #pragma unroll
;                     for (int j = 0; j < 2; ++j) { const f32x2 g = {acc[ai][0][m][n][2 * j], acc[ai][0][m][n][2 * j + 1]}, up = {acc[ai][1][m][n][2 * j], acc[ai][1][m][n][2 * j + 1]};
;                         const f32x2 t = g * (-1.44269504089f); f32x2 e; e.x = __builtin_amdgcn_exp2f(t.x); e.y = __builtin_amdgcn_exp2f(t.y);
;                         const f32x2 d = e + 1.0f; f32x2 r; r.x = __builtin_amdgcn_rcpf(d.x); r.y = __builtin_amdgcn_rcpf(d.y);
;                         h[n * 2 + j] = (g * r) * up; }
;                 u32x4 w; w.x = cvt_pk_bf16(h[0].x, h[0].y); w.y = cvt_pk_bf16(h[1].x, h[1].y); w.z = cvt_pk_bf16(h[2].x, h[2].y); w.w = cvt_pk_bf16(h[3].x, h[3].y);
;                 *(u32x4*)rowp = w; }
	global_store_dwordx4 v[178:179], v[172:175], off
	v_pk_mul_f32 v[160:161], v[88:89], s[92:93] op_sel_hi:[1,0]
	v_pk_mul_f32 v[162:163], v[78:79], s[92:93] op_sel_hi:[1,0]
	v_pk_mul_f32 v[158:159], v[86:87], s[92:93] op_sel_hi:[1,0]
	v_pk_mul_f32 v[164:165], v[80:81], s[92:93] op_sel_hi:[1,0]
	v_exp_f32_e32 v158, v158
	v_exp_f32_e32 v159, v159
	v_exp_f32_e32 v160, v160
	v_exp_f32_e32 v161, v161
	v_exp_f32_e32 v162, v162
	v_exp_f32_e32 v163, v163
	v_exp_f32_e32 v164, v164
	v_exp_f32_e32 v165, v165
	v_pk_add_f32 v[158:159], v[158:159], 1.0 op_sel_hi:[1,0]
	v_pk_add_f32 v[160:161], v[160:161], 1.0 op_sel_hi:[1,0]
	v_rcp_f32_e32 v158, v158
	v_rcp_f32_e32 v159, v159
	v_pk_add_f32 v[162:163], v[162:163], 1.0 op_sel_hi:[1,0]
	v_pk_add_f32 v[164:165], v[164:165], 1.0 op_sel_hi:[1,0]
	v_rcp_f32_e32 v160, v160
	v_rcp_f32_e32 v161, v161
	v_rcp_f32_e32 v162, v162
	v_rcp_f32_e32 v163, v163
	v_rcp_f32_e32 v164, v164
	v_rcp_f32_e32 v165, v165
	v_mad_i64_i32 v[156:157], s[18:19], s20, v153, 0
	v_pk_mul_f32 v[158:159], v[86:87], v[158:159]
	v_lshl_add_u64 v[156:157], v[156:157], 1, s[8:9]
	v_pk_mul_f32 v[158:159], v[70:71], v[158:159]
	v_pk_mul_f32 v[160:161], v[88:89], v[160:161]
	v_pk_mul_f32 v[162:163], v[78:79], v[162:163]
	v_pk_mul_f32 v[164:165], v[80:81], v[164:165]
	v_pk_mul_f32 v[160:161], v[72:73], v[160:161]
	v_pk_mul_f32 v[162:163], v[66:67], v[162:163]
	v_pk_mul_f32 v[164:165], v[68:69], v[164:165]
	v_lshl_add_u64 v[166:167], v[156:157], 0, v[142:143]
	v_cvt_pk_bf16_f32 v156, v158, v159
	v_cvt_pk_bf16_f32 v157, v160, v161
	v_cvt_pk_bf16_f32 v158, v162, v163
	v_cvt_pk_bf16_f32 v159, v164, v165
	ds_write_b128 v244, v[156:159]
	v_lshl_add_u64 v[178:179], v[166:167], 0, v[252:253]
	ds_read_b128 v[172:175], v245
	s_waitcnt lgkmcnt(2)
	global_store_dwordx4 v[176:177], v[168:171], off
	v_pk_mul_f32 v[160:161], v[64:65], s[92:93] op_sel_hi:[1,0]
	v_pk_mul_f32 v[162:163], v[58:59], s[92:93] op_sel_hi:[1,0]
	v_pk_mul_f32 v[158:159], v[62:63], s[92:93] op_sel_hi:[1,0]
	v_pk_mul_f32 v[164:165], v[60:61], s[92:93] op_sel_hi:[1,0]
	v_exp_f32_e32 v158, v158
	v_exp_f32_e32 v159, v159
	v_exp_f32_e32 v160, v160
	v_exp_f32_e32 v161, v161
	v_exp_f32_e32 v162, v162
	v_exp_f32_e32 v163, v163
	v_exp_f32_e32 v164, v164
	v_exp_f32_e32 v165, v165
	v_pk_add_f32 v[158:159], v[158:159], 1.0 op_sel_hi:[1,0]
	v_pk_add_f32 v[160:161], v[160:161], 1.0 op_sel_hi:[1,0]
	v_rcp_f32_e32 v158, v158
	v_rcp_f32_e32 v159, v159
	v_pk_add_f32 v[162:163], v[162:163], 1.0 op_sel_hi:[1,0]
	v_pk_add_f32 v[164:165], v[164:165], 1.0 op_sel_hi:[1,0]
	v_rcp_f32_e32 v160, v160
	v_rcp_f32_e32 v161, v161
	v_rcp_f32_e32 v162, v162
	v_rcp_f32_e32 v163, v163
	v_rcp_f32_e32 v164, v164
	v_rcp_f32_e32 v165, v165
	v_mad_i64_i32 v[156:157], s[18:19], s20, v152, 0
	v_pk_mul_f32 v[158:159], v[62:63], v[158:159]
	v_lshl_add_u64 v[156:157], v[156:157], 1, s[8:9]
	v_pk_mul_f32 v[158:159], v[50:51], v[158:159]
	v_pk_mul_f32 v[160:161], v[64:65], v[160:161]
	v_pk_mul_f32 v[162:163], v[58:59], v[162:163]
	v_pk_mul_f32 v[164:165], v[60:61], v[164:165]
	v_pk_mul_f32 v[160:161], v[52:53], v[160:161]
	v_pk_mul_f32 v[162:163], v[42:43], v[162:163]
	v_pk_mul_f32 v[164:165], v[44:45], v[164:165]
	v_lshl_add_u64 v[166:167], v[156:157], 0, v[142:143]
	v_cvt_pk_bf16_f32 v156, v158, v159
	v_cvt_pk_bf16_f32 v157, v160, v161
	v_cvt_pk_bf16_f32 v158, v162, v163
	v_cvt_pk_bf16_f32 v159, v164, v165
	ds_write_b128 v244, v[156:159]
	v_lshl_add_u64 v[176:177], v[166:167], 0, v[252:253]
	ds_read_b128 v[168:171], v245
	s_waitcnt lgkmcnt(2)
	global_store_dwordx4 v[178:179], v[172:175], off
	v_pk_mul_f32 v[160:161], v[56:57], s[92:93] op_sel_hi:[1,0]
	v_pk_mul_f32 v[162:163], v[46:47], s[92:93] op_sel_hi:[1,0]
	v_pk_mul_f32 v[158:159], v[54:55], s[92:93] op_sel_hi:[1,0]
	v_pk_mul_f32 v[164:165], v[48:49], s[92:93] op_sel_hi:[1,0]
	v_exp_f32_e32 v158, v158
	v_exp_f32_e32 v159, v159
	v_exp_f32_e32 v160, v160
	v_exp_f32_e32 v161, v161
	v_exp_f32_e32 v162, v162
	v_exp_f32_e32 v163, v163
	v_exp_f32_e32 v164, v164
	v_exp_f32_e32 v165, v165
	v_pk_add_f32 v[158:159], v[158:159], 1.0 op_sel_hi:[1,0]
	v_pk_add_f32 v[160:161], v[160:161], 1.0 op_sel_hi:[1,0]
	v_rcp_f32_e32 v158, v158
	v_rcp_f32_e32 v159, v159
	v_pk_add_f32 v[162:163], v[162:163], 1.0 op_sel_hi:[1,0]
	v_pk_add_f32 v[164:165], v[164:165], 1.0 op_sel_hi:[1,0]
	v_rcp_f32_e32 v160, v160
	v_rcp_f32_e32 v161, v161
	v_rcp_f32_e32 v162, v162
	v_rcp_f32_e32 v163, v163
	v_rcp_f32_e32 v164, v164
	v_rcp_f32_e32 v165, v165
	v_mad_i64_i32 v[156:157], s[18:19], s20, v151, 0
	v_pk_mul_f32 v[158:159], v[54:55], v[158:159]
	v_lshl_add_u64 v[156:157], v[156:157], 1, s[8:9]
	v_pk_mul_f32 v[158:159], v[34:35], v[158:159]
	v_pk_mul_f32 v[160:161], v[56:57], v[160:161]
	v_pk_mul_f32 v[162:163], v[46:47], v[162:163]
	v_pk_mul_f32 v[164:165], v[48:49], v[164:165]
	v_pk_mul_f32 v[160:161], v[36:37], v[160:161]
	v_pk_mul_f32 v[162:163], v[26:27], v[162:163]
	v_pk_mul_f32 v[164:165], v[28:29], v[164:165]
	v_lshl_add_u64 v[166:167], v[156:157], 0, v[142:143]
	v_cvt_pk_bf16_f32 v156, v158, v159
	v_cvt_pk_bf16_f32 v157, v160, v161
	v_cvt_pk_bf16_f32 v158, v162, v163
	v_cvt_pk_bf16_f32 v159, v164, v165
	ds_write_b128 v244, v[156:159]
	v_lshl_add_u64 v[178:179], v[166:167], 0, v[252:253]
	ds_read_b128 v[172:175], v245
	s_waitcnt lgkmcnt(2)
; __device__ __forceinline__ unsigned cvt_pk_bf16(float lo, float hi) { unsigned r; asm volatile("v_cvt_pk_bf16_f32 %0, %1, %2" : "=v"(r) : "v"(lo), "v"(hi)); return r; }
;     __device__ __forceinline__ void operator()(const f32x4 (&acc)[2][2][4][2], const Unit& u, int wr, int wc, int fr, int fq) const {
;     ...
;         const int col0 = u.pn * HALF + wc * 32 + 8 * fq;
; #pragma unroll
;         for (int ai = 0; ai < 2; ++ai)
; #pragma unroll
;             for (int m = 0; m < 4; ++m) { bf16_t* rowp = O + (size_t)(row0 + ai * HALF + m * 16) * ldc + col0;
;                 f32x2 h[4];
; #pragma unroll
;                 for (int n = 0; n < 2; ++n)
; #pragma unroll
;                     for (int j = 0; j < 2; ++j) { const f32x2 g = {acc[ai][0][m][n][2 * j], acc[ai][0][m][n][2 * j + 1]}, up = {acc[ai][1][m][n][2 * j], acc[ai][1][m][n][2 * j + 1]};
;                         const f32x2 t = g * (-1.44269504089f); f32x2 e; e.x = __builtin_amdgcn_exp2f(t.x); e.y = __builtin_amdgcn_exp2f(t.y);
;                         const f32x2 d = e + 1.0f; f32x2 r; r.x = __builtin_amdgcn_rcpf(d.x); r.y = __builtin_amdgcn_rcpf(d.y);
;                         h[n * 2 + j] = (g * r) * up; }
;                 u32x4 w; w.x = cvt_pk_bf16(h[0].x, h[0].y); w.y = cvt_pk_bf16(h[1].x, h[1].y); w.z = cvt_pk_bf16(h[2].x, h[2].y); w.w = cvt_pk_bf16(h[3].x, h[3].y);
;                 *(u32x4*)rowp = w; }
	global_store_dwordx4 v[176:177], v[168:171], off
	v_pk_mul_f32 v[160:161], v[40:41], s[92:93] op_sel_hi:[1,0]
	v_pk_mul_f32 v[162:163], v[30:31], s[92:93] op_sel_hi:[1,0]
	v_pk_mul_f32 v[158:159], v[38:39], s[92:93] op_sel_hi:[1,0]
	v_pk_mul_f32 v[164:165], v[32:33], s[92:93] op_sel_hi:[1,0]
	v_exp_f32_e32 v158, v158
	v_exp_f32_e32 v159, v159
	v_exp_f32_e32 v160, v160
	v_exp_f32_e32 v161, v161
	v_exp_f32_e32 v162, v162
	v_exp_f32_e32 v163, v163
	v_exp_f32_e32 v164, v164
	v_exp_f32_e32 v165, v165
	v_pk_add_f32 v[158:159], v[158:159], 1.0 op_sel_hi:[1,0]
	v_pk_add_f32 v[160:161], v[160:161], 1.0 op_sel_hi:[1,0]
	v_rcp_f32_e32 v158, v158
	v_rcp_f32_e32 v159, v159
	v_pk_add_f32 v[162:163], v[162:163], 1.0 op_sel_hi:[1,0]
	v_pk_add_f32 v[164:165], v[164:165], 1.0 op_sel_hi:[1,0]
	v_rcp_f32_e32 v160, v160
	v_rcp_f32_e32 v161, v161
	v_rcp_f32_e32 v162, v162
	v_rcp_f32_e32 v163, v163
	v_rcp_f32_e32 v164, v164
	v_rcp_f32_e32 v165, v165
	v_mad_i64_i32 v[156:157], s[18:19], s20, v150, 0
	v_pk_mul_f32 v[158:159], v[38:39], v[158:159]
	v_lshl_add_u64 v[156:157], v[156:157], 1, s[8:9]
	v_pk_mul_f32 v[158:159], v[18:19], v[158:159]
	v_pk_mul_f32 v[160:161], v[40:41], v[160:161]
	v_pk_mul_f32 v[162:163], v[30:31], v[162:163]
	v_pk_mul_f32 v[164:165], v[32:33], v[164:165]
	v_pk_mul_f32 v[160:161], v[20:21], v[160:161]
	v_pk_mul_f32 v[162:163], v[10:11], v[162:163]
	v_pk_mul_f32 v[164:165], v[12:13], v[164:165]
	v_lshl_add_u64 v[166:167], v[156:157], 0, v[142:143]
	v_cvt_pk_bf16_f32 v156, v158, v159
	v_cvt_pk_bf16_f32 v157, v160, v161
	v_cvt_pk_bf16_f32 v158, v162, v163
	v_cvt_pk_bf16_f32 v159, v164, v165
	ds_write_b128 v244, v[156:159]
	v_lshl_add_u64 v[176:177], v[166:167], 0, v[252:253]
	ds_read_b128 v[168:171], v245
	s_waitcnt lgkmcnt(2)
	global_store_dwordx4 v[178:179], v[172:175], off
	v_pk_mul_f32 v[160:161], v[24:25], s[92:93] op_sel_hi:[1,0]
	v_pk_mul_f32 v[162:163], v[14:15], s[92:93] op_sel_hi:[1,0]
	v_pk_mul_f32 v[158:159], v[22:23], s[92:93] op_sel_hi:[1,0]
	v_pk_mul_f32 v[164:165], v[16:17], s[92:93] op_sel_hi:[1,0]
	v_exp_f32_e32 v158, v158
	v_exp_f32_e32 v159, v159
	v_exp_f32_e32 v160, v160
	v_exp_f32_e32 v161, v161
	v_exp_f32_e32 v162, v162
	v_exp_f32_e32 v163, v163
	v_exp_f32_e32 v164, v164
	v_exp_f32_e32 v165, v165
	v_pk_add_f32 v[158:159], v[158:159], 1.0 op_sel_hi:[1,0]
	v_pk_add_f32 v[160:161], v[160:161], 1.0 op_sel_hi:[1,0]
	v_rcp_f32_e32 v158, v158
	v_rcp_f32_e32 v159, v159
	v_pk_add_f32 v[162:163], v[162:163], 1.0 op_sel_hi:[1,0]
	v_pk_add_f32 v[164:165], v[164:165], 1.0 op_sel_hi:[1,0]
	v_rcp_f32_e32 v160, v160
	v_rcp_f32_e32 v161, v161
	v_rcp_f32_e32 v162, v162
	v_rcp_f32_e32 v163, v163
	v_rcp_f32_e32 v164, v164
	v_rcp_f32_e32 v165, v165
	v_mad_i64_i32 v[156:157], s[18:19], s20, v149, 0
	v_lshl_add_u64 v[156:157], v[156:157], 1, s[8:9]
	v_pk_mul_f32 v[158:159], v[22:23], v[158:159]
	v_pk_mul_f32 v[160:161], v[24:25], v[160:161]
	v_pk_mul_f32 v[158:159], v[6:7], v[158:159]
	v_pk_mul_f32 v[162:163], v[14:15], v[162:163]
	v_pk_mul_f32 v[164:165], v[16:17], v[164:165]
	v_lshl_add_u64 v[142:143], v[156:157], 0, v[142:143]
	v_pk_mul_f32 v[160:161], v[8:9], v[160:161]
	v_pk_mul_f32 v[162:163], v[2:3], v[162:163]
	v_pk_mul_f32 v[164:165], v[4:5], v[164:165]
	v_cvt_pk_bf16_f32 v156, v158, v159
	v_cvt_pk_bf16_f32 v157, v160, v161
	v_cvt_pk_bf16_f32 v158, v162, v163
	s_mov_b64 s[38:39], 0
	v_cvt_pk_bf16_f32 v159, v164, v165
	ds_write_b128 v244, v[156:159]
	v_lshl_add_u64 v[178:179], v[142:143], 0, v[252:253]
	ds_read_b128 v[172:175], v245
	s_waitcnt lgkmcnt(2)
	global_store_dwordx4 v[176:177], v[168:171], off
	s_waitcnt lgkmcnt(0)
	global_store_dwordx4 v[178:179], v[172:175], off
; __device__ __forceinline__ unsigned cvt_pk_bf16(float lo, float hi) { unsigned r; asm volatile("v_cvt_pk_bf16_f32 %0, %1, %2" : "=v"(r) : "v"(lo), "v"(hi)); return r; }
;     __device__ __forceinline__ void operator()(const f32x4 (&acc)[2][2][4][2], const Unit& u, int wr, int wc, int fr, int fq) const {
;     ...
;         if (!swiglu) {
;             const int col0 = u.pn * BM + wc * 32 + 8 * fq;
; #pragma unroll
;             for (int ai = 0; ai < 2; ++ai)
; #pragma unroll
;                 for (int m = 0; m < 4; ++m) { bf16_t* rowp = O + (size_t)(row0 + ai * HALF + m * 16) * ldc + col0;
; #pragma unroll
;                     for (int bj = 0; bj < 2; ++bj) { const f32x4 v0 = acc[ai][bj][m][0], v1 = acc[ai][bj][m][1];
;                         u32x4 w; w.x = cvt_pk_bf16(v0[0], v0[1]); w.y = cvt_pk_bf16(v0[2], v0[3]); w.z = cvt_pk_bf16(v1[0], v1[1]); w.w = cvt_pk_bf16(v1[2], v1[3]);
;                         *(u32x4*)(rowp + bj * HALF) = w; } }
;             return;
.LBB0_365:
	s_andn2_b64 vcc, exec, s[38:39]
	s_cbranch_vccnz .LBB0_367
	v_lshl_or_b32 v142, s67, 8, v146
	v_ashrrev_i32_e32 v143, 31, v142
	v_lshlrev_b64 v[142:143], 1, v[142:143]
	v_lshl_add_u64 v[140:141], v[140:141], 0, v[142:143]
	v_cvt_pk_bf16_f32 v156, v126, v127
	v_cvt_pk_bf16_f32 v157, v128, v129
	v_cvt_pk_bf16_f32 v158, v122, v123
	v_cvt_pk_bf16_f32 v159, v124, v125
	ds_write_b128 v244, v[156:159]
	v_lshl_add_u64 v[176:177], v[140:141], 0, v[252:253]
	ds_read_b128 v[168:171], v245
	s_nop 1
	v_cvt_pk_bf16_f32 v156, v114, v115
	v_cvt_pk_bf16_f32 v157, v116, v117
	v_cvt_pk_bf16_f32 v158, v106, v107
	v_cvt_pk_bf16_f32 v159, v108, v109
	ds_write_b128 v244, v[156:159]
	v_lshl_add_u64 v[178:179], v[140:141], 0, v[252:253]
	ds_read_b128 v[172:175], v245
	s_waitcnt lgkmcnt(2)
	global_store_dwordx4 v[176:177], v[168:171], off
	v_mad_i64_i32 v[140:141], s[18:19], s20, v155, 0
	v_lshl_add_u64 v[140:141], v[140:141], 1, s[8:9]
	v_lshl_add_u64 v[140:141], v[140:141], 0, v[142:143]
	v_cvt_pk_bf16_f32 v156, v118, v119
	v_cvt_pk_bf16_f32 v157, v120, v121
	v_cvt_pk_bf16_f32 v158, v110, v111
	v_cvt_pk_bf16_f32 v159, v112, v113
	ds_write_b128 v244, v[156:159]
	v_lshl_add_u64 v[176:177], v[140:141], 0, v[252:253]
	ds_read_b128 v[168:171], v245
	s_waitcnt lgkmcnt(2)
	global_store_dwordx4 v[178:179], v[172:175], off offset:256
	s_nop 1
	v_cvt_pk_bf16_f32 v156, v98, v99
	v_cvt_pk_bf16_f32 v157, v100, v101
	v_cvt_pk_bf16_f32 v158, v90, v91
	v_cvt_pk_bf16_f32 v159, v92, v93
	ds_write_b128 v244, v[156:159]
	v_lshl_add_u64 v[178:179], v[140:141], 0, v[252:253]
	ds_read_b128 v[172:175], v245
	s_waitcnt lgkmcnt(2)
	global_store_dwordx4 v[176:177], v[168:171], off
	v_mad_i64_i32 v[140:141], s[18:19], s20, v154, 0
	v_lshl_add_u64 v[140:141], v[140:141], 1, s[8:9]
	v_lshl_add_u64 v[140:141], v[140:141], 0, v[142:143]
	v_cvt_pk_bf16_f32 v154, v102, v103
	v_cvt_pk_bf16_f32 v155, v104, v105
	v_cvt_pk_bf16_f32 v156, v94, v95
	v_cvt_pk_bf16_f32 v157, v96, v97
	ds_write_b128 v244, v[154:157]
	v_lshl_add_u64 v[176:177], v[140:141], 0, v[252:253]
	ds_read_b128 v[168:171], v245
	s_waitcnt lgkmcnt(2)
	global_store_dwordx4 v[178:179], v[172:175], off offset:256
	s_nop 1
	v_cvt_pk_bf16_f32 v154, v82, v83
	v_cvt_pk_bf16_f32 v155, v84, v85
	v_cvt_pk_bf16_f32 v156, v74, v75
	v_cvt_pk_bf16_f32 v157, v76, v77
	ds_write_b128 v244, v[154:157]
	v_lshl_add_u64 v[178:179], v[140:141], 0, v[252:253]
	ds_read_b128 v[172:175], v245
	s_waitcnt lgkmcnt(2)
	global_store_dwordx4 v[176:177], v[168:171], off
	v_mad_i64_i32 v[140:141], s[18:19], s20, v153, 0
	v_lshl_add_u64 v[140:141], v[140:141], 1, s[8:9]
	v_lshl_add_u64 v[140:141], v[140:141], 0, v[142:143]
	v_cvt_pk_bf16_f32 v154, v86, v87
	v_cvt_pk_bf16_f32 v155, v88, v89
	v_cvt_pk_bf16_f32 v156, v78, v79
	v_cvt_pk_bf16_f32 v157, v80, v81
	ds_write_b128 v244, v[154:157]
	v_lshl_add_u64 v[176:177], v[140:141], 0, v[252:253]
	ds_read_b128 v[168:171], v245
	s_waitcnt lgkmcnt(2)
	global_store_dwordx4 v[178:179], v[172:175], off offset:256
	s_nop 1
	v_cvt_pk_bf16_f32 v154, v70, v71
	v_cvt_pk_bf16_f32 v155, v72, v73
	v_cvt_pk_bf16_f32 v156, v66, v67
	v_cvt_pk_bf16_f32 v157, v68, v69
	ds_write_b128 v244, v[154:157]
	v_lshl_add_u64 v[178:179], v[140:141], 0, v[252:253]
	ds_read_b128 v[172:175], v245
	s_waitcnt lgkmcnt(2)
	global_store_dwordx4 v[176:177], v[168:171], off
	v_mad_i64_i32 v[140:141], s[18:19], s20, v152, 0
	v_lshl_add_u64 v[140:141], v[140:141], 1, s[8:9]
	v_lshl_add_u64 v[140:141], v[140:141], 0, v[142:143]
	v_cvt_pk_bf16_f32 v152, v62, v63
	v_cvt_pk_bf16_f32 v153, v64, v65
	v_cvt_pk_bf16_f32 v154, v58, v59
	v_cvt_pk_bf16_f32 v155, v60, v61
	ds_write_b128 v244, v[152:155]
	v_lshl_add_u64 v[176:177], v[140:141], 0, v[252:253]
	ds_read_b128 v[168:171], v245
	s_waitcnt lgkmcnt(2)
	global_store_dwordx4 v[178:179], v[172:175], off offset:256
	s_nop 1
	v_cvt_pk_bf16_f32 v152, v50, v51
	v_cvt_pk_bf16_f32 v153, v52, v53
	v_cvt_pk_bf16_f32 v154, v42, v43
	v_cvt_pk_bf16_f32 v155, v44, v45
	ds_write_b128 v244, v[152:155]
	v_lshl_add_u64 v[178:179], v[140:141], 0, v[252:253]
	ds_read_b128 v[172:175], v245
	s_waitcnt lgkmcnt(2)
	global_store_dwordx4 v[176:177], v[168:171], off
	v_mad_i64_i32 v[140:141], s[18:19], s20, v151, 0
	v_lshl_add_u64 v[140:141], v[140:141], 1, s[8:9]
	v_lshl_add_u64 v[140:141], v[140:141], 0, v[142:143]
	v_cvt_pk_bf16_f32 v152, v54, v55
	v_cvt_pk_bf16_f32 v153, v56, v57
	v_cvt_pk_bf16_f32 v154, v46, v47
	v_cvt_pk_bf16_f32 v155, v48, v49
	ds_write_b128 v244, v[152:155]
	v_lshl_add_u64 v[176:177], v[140:141], 0, v[252:253]
	ds_read_b128 v[168:171], v245
	s_waitcnt lgkmcnt(2)
	global_store_dwordx4 v[178:179], v[172:175], off offset:256
	s_nop 1
	v_cvt_pk_bf16_f32 v152, v34, v35
	v_cvt_pk_bf16_f32 v153, v36, v37
	v_cvt_pk_bf16_f32 v154, v26, v27
	v_cvt_pk_bf16_f32 v155, v28, v29
	ds_write_b128 v244, v[152:155]
	v_lshl_add_u64 v[178:179], v[140:141], 0, v[252:253]
	ds_read_b128 v[172:175], v245
	s_waitcnt lgkmcnt(2)
	global_store_dwordx4 v[176:177], v[168:171], off
	v_mad_i64_i32 v[140:141], s[18:19], s20, v150, 0
	v_lshl_add_u64 v[140:141], v[140:141], 1, s[8:9]
	v_lshl_add_u64 v[140:141], v[140:141], 0, v[142:143]
	v_cvt_pk_bf16_f32 v150, v38, v39
	v_cvt_pk_bf16_f32 v151, v40, v41
	v_cvt_pk_bf16_f32 v152, v30, v31
	v_cvt_pk_bf16_f32 v153, v32, v33
	ds_write_b128 v244, v[150:153]
	v_lshl_add_u64 v[176:177], v[140:141], 0, v[252:253]
	ds_read_b128 v[168:171], v245
	s_waitcnt lgkmcnt(2)
	global_store_dwordx4 v[178:179], v[172:175], off offset:256
	s_nop 1
	v_cvt_pk_bf16_f32 v150, v18, v19
	v_cvt_pk_bf16_f32 v151, v20, v21
	v_cvt_pk_bf16_f32 v152, v10, v11
	v_cvt_pk_bf16_f32 v153, v12, v13
	ds_write_b128 v244, v[150:153]
	v_lshl_add_u64 v[178:179], v[140:141], 0, v[252:253]
	ds_read_b128 v[172:175], v245
	s_waitcnt lgkmcnt(2)
	global_store_dwordx4 v[176:177], v[168:171], off
	v_mad_i64_i32 v[140:141], s[18:19], s20, v149, 0
	v_lshl_add_u64 v[140:141], v[140:141], 1, s[8:9]
	v_lshl_add_u64 v[150:151], v[140:141], 0, v[142:143]
	v_cvt_pk_bf16_f32 v140, v22, v23
	v_cvt_pk_bf16_f32 v141, v24, v25
	v_cvt_pk_bf16_f32 v142, v14, v15
	v_cvt_pk_bf16_f32 v143, v16, v17
	ds_write_b128 v244, v[140:143]
	v_lshl_add_u64 v[176:177], v[150:151], 0, v[252:253]
	ds_read_b128 v[168:171], v245
	s_waitcnt lgkmcnt(2)
	global_store_dwordx4 v[178:179], v[172:175], off offset:256
	s_nop 1
	v_cvt_pk_bf16_f32 v140, v6, v7
	v_cvt_pk_bf16_f32 v141, v8, v9
	v_cvt_pk_bf16_f32 v142, v2, v3
	v_cvt_pk_bf16_f32 v143, v4, v5
	ds_write_b128 v244, v[140:143]
	v_lshl_add_u64 v[178:179], v[150:151], 0, v[252:253]
	ds_read_b128 v[172:175], v245
	s_waitcnt lgkmcnt(2)
	global_store_dwordx4 v[176:177], v[168:171], off
	s_waitcnt lgkmcnt(0)
	global_store_dwordx4 v[178:179], v[172:175], off offset:256

; __device__ __forceinline__ unsigned cvt_pk_bf16(float lo, float hi) { unsigned r; asm volatile("v_cvt_pk_bf16_f32 %0, %1, %2" : "=v"(r) : "v"(lo), "v"(hi)); return r; }
;     __device__ __forceinline__ void operator()(const f32x4 (&acc)[2][2][4][2], const Unit& u, int wr, int wc, int fr, int fq) const {
;     ...
;         if (u.part >= 0) {
;             bf16_t* Pp = P + (size_t)u.part * pstride; const int col0 = u.pn * BM + wc * 32 + 8 * fq;
; #pragma unroll
;             for (int ai = 0; ai < 2; ++ai)
; #pragma unroll
;                 for (int m = 0; m < 4; ++m) { bf16_t* rowp = Pp + (size_t)(row0 + ai * HALF + m * 16 - prow0) * ldc + col0;
; #pragma unroll
;                     for (int bj = 0; bj < 2; ++bj) { const f32x4 v0 = acc[ai][bj][m][0], v1 = acc[ai][bj][m][1];
;                         u32x4 w; w.x = cvt_pk_bf16(v0[0], v0[1]); w.y = cvt_pk_bf16(v0[2], v0[3]); w.z = cvt_pk_bf16(v1[0], v1[1]); w.w = cvt_pk_bf16(v1[2], v1[3]);
;                         *(u32x4*)(rowp + bj * HALF) = w; } }
;             return;
.LBB0_370:
	s_mov_b32 s31, s89
	s_lshl_b64 s[18:19], s[30:31], 23
	s_add_u32 s18, s70, s18
	v_lshl_or_b32 v140, s67, 8, v146
	s_addc_u32 s19, s71, s19
	v_ashrrev_i32_e32 v141, 31, v140
	v_add_u32_e32 v142, 0xffffc000, v148
	v_lshl_add_u64 v[140:141], v[140:141], 1, s[18:19]
	v_mad_i64_i32 v[142:143], s[18:19], s20, v142, 0
	v_lshl_add_u64 v[142:143], v[142:143], 1, v[140:141]
	v_cvt_pk_bf16_f32 v126, v126, v127
	v_cvt_pk_bf16_f32 v127, v128, v129
	v_cvt_pk_bf16_f32 v128, v122, v123
	v_cvt_pk_bf16_f32 v129, v124, v125
	ds_write_b128 v244, v[126:129]
	v_lshl_add_u64 v[176:177], v[142:143], 0, v[252:253]
	ds_read_b128 v[168:171], v245
	v_cvt_pk_bf16_f32 v114, v114, v115
	v_cvt_pk_bf16_f32 v115, v116, v117
	v_cvt_pk_bf16_f32 v116, v106, v107
	v_add_u32_e32 v106, 0xffffc010, v148
	v_mad_i64_i32 v[106:107], s[18:19], s20, v106, 0
	v_cvt_pk_bf16_f32 v117, v108, v109
	ds_write_b128 v244, v[114:117]
	v_lshl_add_u64 v[178:179], v[142:143], 0, v[252:253]
	ds_read_b128 v[172:175], v245
	s_waitcnt lgkmcnt(2)
	global_store_dwordx4 v[176:177], v[168:171], off
	s_nop 1
	v_lshl_add_u64 v[114:115], v[106:107], 1, v[140:141]
	v_cvt_pk_bf16_f32 v106, v118, v119
	v_cvt_pk_bf16_f32 v107, v120, v121
	v_cvt_pk_bf16_f32 v108, v110, v111
	v_cvt_pk_bf16_f32 v109, v112, v113
	ds_write_b128 v244, v[106:109]
	v_lshl_add_u64 v[176:177], v[114:115], 0, v[252:253]
	ds_read_b128 v[168:171], v245
	s_waitcnt lgkmcnt(2)
	global_store_dwordx4 v[178:179], v[172:175], off offset:256
	v_cvt_pk_bf16_f32 v98, v98, v99
	v_cvt_pk_bf16_f32 v99, v100, v101
	v_cvt_pk_bf16_f32 v100, v90, v91
	v_add_u32_e32 v90, 0xffffc020, v148
	v_mad_i64_i32 v[90:91], s[18:19], s20, v90, 0
	v_cvt_pk_bf16_f32 v101, v92, v93
	ds_write_b128 v244, v[98:101]
	v_lshl_add_u64 v[178:179], v[114:115], 0, v[252:253]
	ds_read_b128 v[172:175], v245
	s_waitcnt lgkmcnt(2)
	global_store_dwordx4 v[176:177], v[168:171], off
	s_nop 1
	v_lshl_add_u64 v[98:99], v[90:91], 1, v[140:141]
	v_cvt_pk_bf16_f32 v90, v102, v103
	v_cvt_pk_bf16_f32 v91, v104, v105
	v_cvt_pk_bf16_f32 v92, v94, v95
	v_cvt_pk_bf16_f32 v93, v96, v97
	ds_write_b128 v244, v[90:93]
	v_lshl_add_u64 v[176:177], v[98:99], 0, v[252:253]
	ds_read_b128 v[168:171], v245
	s_waitcnt lgkmcnt(2)
	global_store_dwordx4 v[178:179], v[172:175], off offset:256
	v_cvt_pk_bf16_f32 v82, v82, v83
	v_cvt_pk_bf16_f32 v83, v84, v85
	v_cvt_pk_bf16_f32 v84, v74, v75
	v_add_u32_e32 v74, 0xffffc030, v148
	v_mad_i64_i32 v[74:75], s[18:19], s20, v74, 0
	v_cvt_pk_bf16_f32 v85, v76, v77
	ds_write_b128 v244, v[82:85]
	v_lshl_add_u64 v[178:179], v[98:99], 0, v[252:253]
	ds_read_b128 v[172:175], v245
	s_waitcnt lgkmcnt(2)
	global_store_dwordx4 v[176:177], v[168:171], off
	s_nop 1
	v_lshl_add_u64 v[82:83], v[74:75], 1, v[140:141]
	v_cvt_pk_bf16_f32 v74, v86, v87
	v_cvt_pk_bf16_f32 v75, v88, v89
	v_cvt_pk_bf16_f32 v76, v78, v79
	v_cvt_pk_bf16_f32 v77, v80, v81
	ds_write_b128 v244, v[74:77]
	v_lshl_add_u64 v[176:177], v[82:83], 0, v[252:253]
	ds_read_b128 v[168:171], v245
	s_waitcnt lgkmcnt(2)
	global_store_dwordx4 v[178:179], v[172:175], off offset:256
	v_cvt_pk_bf16_f32 v70, v70, v71
	v_cvt_pk_bf16_f32 v71, v72, v73
	v_cvt_pk_bf16_f32 v72, v66, v67
	v_add_u32_e32 v66, 0xffffc080, v148
	v_mad_i64_i32 v[66:67], s[18:19], s20, v66, 0
	v_lshl_add_u64 v[66:67], v[66:67], 1, v[140:141]
	v_cvt_pk_bf16_f32 v73, v68, v69
	ds_write_b128 v244, v[70:73]
	v_lshl_add_u64 v[178:179], v[82:83], 0, v[252:253]
	ds_read_b128 v[172:175], v245
	s_waitcnt lgkmcnt(2)
	global_store_dwordx4 v[176:177], v[168:171], off
	v_cvt_pk_bf16_f32 v62, v62, v63
	v_cvt_pk_bf16_f32 v63, v64, v65
	v_cvt_pk_bf16_f32 v64, v58, v59
	v_cvt_pk_bf16_f32 v65, v60, v61
	ds_write_b128 v244, v[62:65]
	v_lshl_add_u64 v[176:177], v[66:67], 0, v[252:253]
	ds_read_b128 v[168:171], v245
	s_waitcnt lgkmcnt(2)
	global_store_dwordx4 v[178:179], v[172:175], off offset:256
	v_cvt_pk_bf16_f32 v50, v50, v51
	v_cvt_pk_bf16_f32 v51, v52, v53
	v_cvt_pk_bf16_f32 v52, v42, v43
	v_add_u32_e32 v42, 0xffffc090, v148
	v_mad_i64_i32 v[42:43], s[18:19], s20, v42, 0
	v_cvt_pk_bf16_f32 v53, v44, v45
	ds_write_b128 v244, v[50:53]
	v_lshl_add_u64 v[178:179], v[66:67], 0, v[252:253]
	ds_read_b128 v[172:175], v245
	s_waitcnt lgkmcnt(2)
	global_store_dwordx4 v[176:177], v[168:171], off
	s_nop 1
	v_lshl_add_u64 v[50:51], v[42:43], 1, v[140:141]
	v_cvt_pk_bf16_f32 v42, v54, v55
	v_cvt_pk_bf16_f32 v43, v56, v57
	v_cvt_pk_bf16_f32 v44, v46, v47
	v_cvt_pk_bf16_f32 v45, v48, v49
	ds_write_b128 v244, v[42:45]
	v_lshl_add_u64 v[176:177], v[50:51], 0, v[252:253]
	ds_read_b128 v[168:171], v245
	s_waitcnt lgkmcnt(2)
	global_store_dwordx4 v[178:179], v[172:175], off offset:256
	v_cvt_pk_bf16_f32 v34, v34, v35
	v_cvt_pk_bf16_f32 v35, v36, v37
	v_cvt_pk_bf16_f32 v36, v26, v27
	v_add_u32_e32 v26, 0xffffc0a0, v148
	v_mad_i64_i32 v[26:27], s[18:19], s20, v26, 0
	v_cvt_pk_bf16_f32 v37, v28, v29
	ds_write_b128 v244, v[34:37]
	v_lshl_add_u64 v[178:179], v[50:51], 0, v[252:253]
	ds_read_b128 v[172:175], v245
	s_waitcnt lgkmcnt(2)
	global_store_dwordx4 v[176:177], v[168:171], off
	s_nop 1
	v_lshl_add_u64 v[34:35], v[26:27], 1, v[140:141]
	v_cvt_pk_bf16_f32 v26, v38, v39
	v_cvt_pk_bf16_f32 v27, v40, v41
	v_cvt_pk_bf16_f32 v28, v30, v31
	v_cvt_pk_bf16_f32 v29, v32, v33
	ds_write_b128 v244, v[26:29]
	v_lshl_add_u64 v[176:177], v[34:35], 0, v[252:253]
	ds_read_b128 v[168:171], v245
	s_waitcnt lgkmcnt(2)
	global_store_dwordx4 v[178:179], v[172:175], off offset:256
	v_cvt_pk_bf16_f32 v18, v18, v19
	v_cvt_pk_bf16_f32 v19, v20, v21
	v_cvt_pk_bf16_f32 v20, v10, v11
	v_add_u32_e32 v10, 0xffffc0b0, v148
	v_mad_i64_i32 v[10:11], s[18:19], s20, v10, 0
	v_cvt_pk_bf16_f32 v21, v12, v13
	ds_write_b128 v244, v[18:21]
	v_lshl_add_u64 v[178:179], v[34:35], 0, v[252:253]
	ds_read_b128 v[172:175], v245
	s_waitcnt lgkmcnt(2)
	global_store_dwordx4 v[176:177], v[168:171], off
	s_nop 1
	v_lshl_add_u64 v[18:19], v[10:11], 1, v[140:141]
	v_cvt_pk_bf16_f32 v10, v22, v23
	v_cvt_pk_bf16_f32 v11, v24, v25
	v_cvt_pk_bf16_f32 v12, v14, v15
	v_cvt_pk_bf16_f32 v13, v16, v17
	ds_write_b128 v244, v[10:13]
	v_lshl_add_u64 v[176:177], v[18:19], 0, v[252:253]
	ds_read_b128 v[168:171], v245
	s_waitcnt lgkmcnt(2)
	global_store_dwordx4 v[178:179], v[172:175], off offset:256
	v_cvt_pk_bf16_f32 v6, v6, v7
	v_cvt_pk_bf16_f32 v7, v8, v9
	v_cvt_pk_bf16_f32 v8, v2, v3
	v_cvt_pk_bf16_f32 v9, v4, v5
	ds_write_b128 v244, v[6:9]
	v_lshl_add_u64 v[178:179], v[18:19], 0, v[252:253]
	ds_read_b128 v[172:175], v245
	s_waitcnt lgkmcnt(2)
	global_store_dwordx4 v[176:177], v[168:171], off
	s_and_b64 vcc, exec, s[40:41]
	s_mov_b64 s[30:31], -1
	s_waitcnt lgkmcnt(0)
	global_store_dwordx4 v[178:179], v[172:175], off offset:256
	s_cbranch_vccnz .LBB0_345
